# v32 + early compute-segment barrier also in the KV-projection and attention-score GEMM loops
# speedup vs baseline: 1.0038x; 1.0038x over previous
; #define PG8_STAGE(bufoff, gbase, voff) do { _Pragma("unroll") for (int _i = 0; _i < 2; ++_i) \
;         __builtin_amdgcn_global_load_lds((const unsigned*)((const char*)(gbase) + (voff)[_i]), (LAS unsigned*)(lds + (bufoff) + ldsw + _i * 8192), 16, 0, 0); } while (0)
; #define PG8_LDA(dst, b, h) do { _Pragma("unroll") for (int m = 0; m < 4; ++m) _Pragma("unroll") for (int k = 0; k < 2; ++k) dst[m][k] = *(const LAS bf16x8*)(lds + PG8_SA(b, h) + aoff + m * 2048 + k * 1024); } while (0)
; #define PG8_LDB(dst, b, h) do { _Pragma("unroll") for (int n = 0; n < 2; ++n) _Pragma("unroll") for (int k = 0; k < 2; ++k) dst[n][k] = *(const LAS bf16x8*)(lds + PG8_SB(b, h) + boff + n * 2048 + k * 1024); } while (0)
; #define PG8_MMA(ai, bj, At, Bt) do { __builtin_amdgcn_s_setprio(1); _Pragma("unroll") for (int m = 0; m < 4; ++m) _Pragma("unroll") for (int n = 0; n < 2; ++n) _Pragma("unroll") for (int k = 0; k < 2; ++k) \
;         acc[ai][bj][m][n] = __builtin_amdgcn_mfma_f32_16x16x32_bf16(Bt[n][k], At[m][k], acc[ai][bj][m][n], 0, 0, 0); __builtin_amdgcn_s_setprio(0); } while (0)
; #define PG8_WAIT_V(n) asm volatile("s_waitcnt vmcnt(" #n ")" ::: "memory")
; #define PG8_WAIT_L(n) asm volatile("s_waitcnt lgkmcnt(" #n ")" ::: "memory")
; #define PG8_BAR __builtin_amdgcn_s_barrier()
; #define PG8_SCHED __builtin_amdgcn_sched_barrier(0)
; template <class Epi, class Sched>
; __device__ __forceinline__ void gemm_phase(LAS unsigned char* lds, const Gemm g, Sched S, const Epi& E) {
;     ...
;         for (int t = 0; t < nt; t += 2) {
;             const bool last = (t == nt - 2);
;             const char* a1 = cA + (size_t)(t + 1) * kstep;
;             const char* a2 = last ? nA : cA + (size_t)(t + 2) * kstep; const char* b2 = last ? nB : cB + (size_t)(t + 2) * kstep;
;             const char* a3 = a2 + kstep; const char* b3 = b2 + kstep;
;             PG8_LDB(B0, 0, 0); PG8_LDB(B1, 0, 1); PG8_SCHED; PG8_LDA(At, 0, 0); PG8_STAGE(PG8_SA(1, 1), a1 + hstepA, voffA);
;             PG8_WAIT_V(8); PG8_WAIT_L(0); PG8_BAR; PG8_MMA(0, 0, At, B0); PG8_MMA(0, 1, At, B1); PG8_BAR; PG8_SCHED;
;             PG8_LDA(At, 0, 1); PG8_STAGE(PG8_SB(0, 0), b2, voffB); PG8_STAGE(PG8_SB(0, 1), b2 + hstepB, voffB); PG8_STAGE(PG8_SA(0, 0), a2, voffA);
;             PG8_WAIT_V(8); PG8_WAIT_L(0); PG8_BAR; PG8_MMA(1, 0, At, B0); PG8_MMA(1, 1, At, B1); PG8_BAR; PG8_SCHED;
.LBB0_199:
	ds_read_b128 v[138:141], v152
	ds_read_b128 v[142:145], v152 offset:1024
	ds_read_b128 v[156:159], v152 offset:2048
	ds_read_b128 v[164:167], v152 offset:3072
	ds_read_b128 v[168:171], v153
	ds_read_b128 v[172:175], v153 offset:1024
	ds_read_b128 v[176:179], v153 offset:2048
	ds_read_b128 v[180:183], v153 offset:3072
	s_add_u32 s22, s20, 0xfffc0080
	s_addc_u32 s23, s21, -1
	s_cmp_eq_u32 s57, 12
	s_cselect_b32 s25, s1, s23
	s_cselect_b32 s24, s11, s22
	s_cselect_b32 s23, s53, s56
	s_cselect_b32 s22, s54, s55
	v_lshl_add_u64 v[146:147], s[20:21], 0, v[134:135]
	s_add_i32 m0, s36, 0xc000
	ds_read_b128 v[184:187], v154
	ds_read_b128 v[188:191], v154 offset:1024
	ds_read_b128 v[192:195], v154 offset:2048
	ds_read_b128 v[196:199], v154 offset:3072
	ds_read_b128 v[200:203], v154 offset:4096
	ds_read_b128 v[204:207], v154 offset:5120
	ds_read_b128 v[208:211], v154 offset:6144
	ds_read_b128 v[212:215], v154 offset:7168
	global_load_lds_dwordx4 v[146:147], off
	v_lshl_add_u64 v[146:147], s[20:21], 0, v[136:137]
	s_add_i32 m0, s36, 0xe000
	s_nop 0
	global_load_lds_dwordx4 v[146:147], off
	s_waitcnt vmcnt(8)
	s_waitcnt lgkmcnt(0)
	s_barrier
	s_setprio 1
	s_waitcnt lgkmcnt(0)
	v_mfma_f32_16x16x32_bf16 v[124:127], v[138:141], v[184:187], v[124:127]
	v_mfma_f32_16x16x32_bf16 v[120:123], v[156:159], v[184:187], v[120:123]
	v_mfma_f32_16x16x32_bf16 v[108:111], v[138:141], v[192:195], v[108:111]
	v_mfma_f32_16x16x32_bf16 v[104:107], v[156:159], v[192:195], v[104:107]
	v_mfma_f32_16x16x32_bf16 v[92:95], v[138:141], v[200:203], v[92:95]
	v_mfma_f32_16x16x32_bf16 v[88:91], v[156:159], v[200:203], v[88:91]
	v_mfma_f32_16x16x32_bf16 v[76:79], v[138:141], v[208:211], v[76:79]
	v_mfma_f32_16x16x32_bf16 v[72:75], v[156:159], v[208:211], v[72:75]
	v_mfma_f32_16x16x32_bf16 v[124:127], v[142:145], v[188:191], v[124:127]
	v_mfma_f32_16x16x32_bf16 v[120:123], v[164:167], v[188:191], v[120:123]
	v_mfma_f32_16x16x32_bf16 v[108:111], v[142:145], v[196:199], v[108:111]
	v_mfma_f32_16x16x32_bf16 v[104:107], v[164:167], v[196:199], v[104:107]
	v_mfma_f32_16x16x32_bf16 v[92:95], v[142:145], v[204:207], v[92:95]
	v_mfma_f32_16x16x32_bf16 v[88:91], v[164:167], v[204:207], v[88:91]
	v_mfma_f32_16x16x32_bf16 v[76:79], v[142:145], v[212:215], v[76:79]
	v_mfma_f32_16x16x32_bf16 v[72:75], v[164:167], v[212:215], v[72:75]
	s_setprio 0
	s_setprio 1
	v_mfma_f32_16x16x32_bf16 v[116:119], v[168:171], v[184:187], v[116:119]
	v_mfma_f32_16x16x32_bf16 v[112:115], v[176:179], v[184:187], v[112:115]
	v_mfma_f32_16x16x32_bf16 v[100:103], v[168:171], v[192:195], v[100:103]
	v_mfma_f32_16x16x32_bf16 v[96:99], v[176:179], v[192:195], v[96:99]
	v_mfma_f32_16x16x32_bf16 v[84:87], v[168:171], v[200:203], v[84:87]
	v_mfma_f32_16x16x32_bf16 v[80:83], v[176:179], v[200:203], v[80:83]
	v_mfma_f32_16x16x32_bf16 v[68:71], v[168:171], v[208:211], v[68:71]
	v_mfma_f32_16x16x32_bf16 v[64:67], v[176:179], v[208:211], v[64:67]
	v_mfma_f32_16x16x32_bf16 v[116:119], v[172:175], v[188:191], v[116:119]
	v_mfma_f32_16x16x32_bf16 v[112:115], v[180:183], v[188:191], v[112:115]
	v_mfma_f32_16x16x32_bf16 v[100:103], v[172:175], v[196:199], v[100:103]
	v_mfma_f32_16x16x32_bf16 v[96:99], v[180:183], v[196:199], v[96:99]
	s_setprio 2
	s_barrier
	v_mfma_f32_16x16x32_bf16 v[84:87], v[172:175], v[204:207], v[84:87]
	v_mfma_f32_16x16x32_bf16 v[80:83], v[180:183], v[204:207], v[80:83]
	v_mfma_f32_16x16x32_bf16 v[68:71], v[172:175], v[212:215], v[68:71]
	v_mfma_f32_16x16x32_bf16 v[64:67], v[180:183], v[212:215], v[64:67]
	s_setprio 0
	s_add_i32 s58, s42, s29
	v_lshl_add_u64 v[146:147], s[22:23], 0, v[130:131]
	s_mov_b32 m0, s58
	ds_read_b128 v[184:187], v154 offset:16384
	ds_read_b128 v[188:191], v154 offset:17408
	ds_read_b128 v[192:195], v154 offset:18432
	ds_read_b128 v[196:199], v154 offset:19456
	ds_read_b128 v[200:203], v154 offset:20480
	ds_read_b128 v[204:207], v154 offset:21504
	ds_read_b128 v[208:211], v154 offset:22528
	ds_read_b128 v[212:215], v154 offset:23552
	global_load_lds_dwordx4 v[146:147], off
	s_add_i32 m0, s58, 0x2000
	s_add_u32 s58, s22, 0x40000
	v_lshl_add_u64 v[160:161], s[22:23], 0, v[128:129]
	s_addc_u32 s59, s23, 0
	s_add_i32 s60, s43, s29
	global_load_lds_dwordx4 v[160:161], off
	v_lshl_add_u64 v[216:217], s[58:59], 0, v[130:131]
	s_mov_b32 m0, s60
	v_lshl_add_u64 v[218:219], s[24:25], 0, v[128:129]
	global_load_lds_dwordx4 v[216:217], off
	v_lshl_add_u64 v[216:217], s[58:59], 0, v[128:129]
	s_add_i32 m0, s60, 0x2000
	s_nop 0
	global_load_lds_dwordx4 v[216:217], off
	v_lshl_add_u64 v[216:217], s[24:25], 0, v[130:131]
	s_mov_b32 m0, s36
	s_nop 0
	global_load_lds_dwordx4 v[216:217], off
	s_mov_b32 m0, s37
	s_nop 0
	global_load_lds_dwordx4 v[218:219], off
	s_waitcnt vmcnt(8)
	s_waitcnt lgkmcnt(0)
	s_barrier
; #define PG8_STAGE(bufoff, gbase, voff) do { _Pragma("unroll") for (int _i = 0; _i < 2; ++_i) \
;         __builtin_amdgcn_global_load_lds((const unsigned*)((const char*)(gbase) + (voff)[_i]), (LAS unsigned*)(lds + (bufoff) + ldsw + _i * 8192), 16, 0, 0); } while (0)
; #define PG8_LDA(dst, b, h) do { _Pragma("unroll") for (int m = 0; m < 4; ++m) _Pragma("unroll") for (int k = 0; k < 2; ++k) dst[m][k] = *(const LAS bf16x8*)(lds + PG8_SA(b, h) + aoff + m * 2048 + k * 1024); } while (0)
; #define PG8_LDB(dst, b, h) do { _Pragma("unroll") for (int n = 0; n < 2; ++n) _Pragma("unroll") for (int k = 0; k < 2; ++k) dst[n][k] = *(const LAS bf16x8*)(lds + PG8_SB(b, h) + boff + n * 2048 + k * 1024); } while (0)
; #define PG8_MMA(ai, bj, At, Bt) do { __builtin_amdgcn_s_setprio(1); _Pragma("unroll") for (int m = 0; m < 4; ++m) _Pragma("unroll") for (int n = 0; n < 2; ++n) _Pragma("unroll") for (int k = 0; k < 2; ++k) \
;         acc[ai][bj][m][n] = __builtin_amdgcn_mfma_f32_16x16x32_bf16(Bt[n][k], At[m][k], acc[ai][bj][m][n], 0, 0, 0); __builtin_amdgcn_s_setprio(0); } while (0)
; #define PG8_WAIT_V(n) asm volatile("s_waitcnt vmcnt(" #n ")" ::: "memory")
; #define PG8_WAIT_L(n) asm volatile("s_waitcnt lgkmcnt(" #n ")" ::: "memory")
; #define PG8_BAR __builtin_amdgcn_s_barrier()
; #define PG8_SCHED __builtin_amdgcn_sched_barrier(0)
; template <class Epi, class Sched>
; __device__ __forceinline__ void gemm_phase(LAS unsigned char* lds, const Gemm g, Sched S, const Epi& E) {
;     ...
;             PG8_WAIT_V(8); PG8_WAIT_L(0); PG8_BAR; PG8_MMA(1, 0, At, B0); PG8_MMA(1, 1, At, B1); PG8_BAR; PG8_SCHED;
;             PG8_LDB(B0, 1, 0); PG8_LDB(B1, 1, 1); PG8_SCHED; PG8_LDA(At, 1, 0); PG8_STAGE(PG8_SA(0, 1), a2 + hstepA, voffA);
;             PG8_WAIT_V(8); PG8_WAIT_L(0); PG8_BAR; PG8_MMA(0, 0, At, B0); PG8_MMA(0, 1, At, B1); PG8_BAR; PG8_SCHED;
	s_setprio 1
	s_waitcnt lgkmcnt(0)
	v_mfma_f32_16x16x32_bf16 v[60:63], v[138:141], v[184:187], v[60:63]
	v_mfma_f32_16x16x32_bf16 v[56:59], v[156:159], v[184:187], v[56:59]
	v_mfma_f32_16x16x32_bf16 v[44:47], v[138:141], v[192:195], v[44:47]
	v_mfma_f32_16x16x32_bf16 v[40:43], v[156:159], v[192:195], v[40:43]
	v_mfma_f32_16x16x32_bf16 v[28:31], v[138:141], v[200:203], v[28:31]
	v_mfma_f32_16x16x32_bf16 v[24:27], v[156:159], v[200:203], v[24:27]
	v_mfma_f32_16x16x32_bf16 v[12:15], v[138:141], v[208:211], v[12:15]
	v_mfma_f32_16x16x32_bf16 v[8:11], v[156:159], v[208:211], v[8:11]
	v_mfma_f32_16x16x32_bf16 v[60:63], v[142:145], v[188:191], v[60:63]
	v_mfma_f32_16x16x32_bf16 v[56:59], v[164:167], v[188:191], v[56:59]
	v_mfma_f32_16x16x32_bf16 v[44:47], v[142:145], v[196:199], v[44:47]
	v_mfma_f32_16x16x32_bf16 v[40:43], v[164:167], v[196:199], v[40:43]
	v_mfma_f32_16x16x32_bf16 v[28:31], v[142:145], v[204:207], v[28:31]
	v_mfma_f32_16x16x32_bf16 v[24:27], v[164:167], v[204:207], v[24:27]
	v_mfma_f32_16x16x32_bf16 v[12:15], v[142:145], v[212:215], v[12:15]
	v_mfma_f32_16x16x32_bf16 v[8:11], v[164:167], v[212:215], v[8:11]
	s_setprio 0
	s_setprio 1
	v_mfma_f32_16x16x32_bf16 v[52:55], v[168:171], v[184:187], v[52:55]
	v_mfma_f32_16x16x32_bf16 v[48:51], v[176:179], v[184:187], v[48:51]
	v_mfma_f32_16x16x32_bf16 v[36:39], v[168:171], v[192:195], v[36:39]
	v_mfma_f32_16x16x32_bf16 v[32:35], v[176:179], v[192:195], v[32:35]
	v_mfma_f32_16x16x32_bf16 v[20:23], v[168:171], v[200:203], v[20:23]
	v_mfma_f32_16x16x32_bf16 v[16:19], v[176:179], v[200:203], v[16:19]
	v_mfma_f32_16x16x32_bf16 v[4:7], v[168:171], v[208:211], v[4:7]
	v_mfma_f32_16x16x32_bf16 v[0:3], v[176:179], v[208:211], v[0:3]
	v_mfma_f32_16x16x32_bf16 v[52:55], v[172:175], v[188:191], v[52:55]
	v_mfma_f32_16x16x32_bf16 v[48:51], v[180:183], v[188:191], v[48:51]
	v_mfma_f32_16x16x32_bf16 v[36:39], v[172:175], v[196:199], v[36:39]
	v_mfma_f32_16x16x32_bf16 v[32:35], v[180:183], v[196:199], v[32:35]
	s_setprio 2
	s_barrier
	v_mfma_f32_16x16x32_bf16 v[20:23], v[172:175], v[204:207], v[20:23]
	v_mfma_f32_16x16x32_bf16 v[16:19], v[180:183], v[204:207], v[16:19]
	v_mfma_f32_16x16x32_bf16 v[4:7], v[172:175], v[212:215], v[4:7]
	v_mfma_f32_16x16x32_bf16 v[0:3], v[180:183], v[212:215], v[0:3]
	s_setprio 0
	s_add_i32 s58, 0, 0x18000
	v_add_u32_e32 v132, s58, v150
	s_add_i32 s59, 0, 0x1c000
	ds_read_b128 v[138:141], v132
	ds_read_b128 v[142:145], v132 offset:1024
	ds_read_b128 v[156:159], v132 offset:2048
	ds_read_b128 v[164:167], v132 offset:3072
	v_add_u32_e32 v132, s59, v150
	ds_read_b128 v[168:171], v132
	ds_read_b128 v[172:175], v132 offset:1024
	ds_read_b128 v[176:179], v132 offset:2048
	ds_read_b128 v[180:183], v132 offset:3072
	s_add_u32 s24, s24, 0x40000
	s_addc_u32 s25, s25, 0
	s_mov_b32 m0, s38
	v_lshl_add_u64 v[220:221], s[24:25], 0, v[130:131]
	ds_read_b128 v[184:187], v154 offset:32768
	ds_read_b128 v[188:191], v154 offset:33792
	ds_read_b128 v[192:195], v154 offset:34816
	ds_read_b128 v[196:199], v154 offset:35840
	ds_read_b128 v[200:203], v154 offset:36864
	ds_read_b128 v[204:207], v154 offset:37888
	ds_read_b128 v[208:211], v154 offset:38912
	ds_read_b128 v[212:215], v154 offset:39936
	global_load_lds_dwordx4 v[220:221], off
	v_lshl_add_u64 v[220:221], s[24:25], 0, v[128:129]
	s_mov_b32 m0, s39
	s_nop 0
	global_load_lds_dwordx4 v[220:221], off
	s_waitcnt vmcnt(8)
	s_waitcnt lgkmcnt(0)
	s_barrier
	s_setprio 1
	s_waitcnt lgkmcnt(0)
	v_mfma_f32_16x16x32_bf16 v[124:127], v[138:141], v[184:187], v[124:127]
	v_mfma_f32_16x16x32_bf16 v[120:123], v[156:159], v[184:187], v[120:123]
	v_mfma_f32_16x16x32_bf16 v[108:111], v[138:141], v[192:195], v[108:111]
	v_mfma_f32_16x16x32_bf16 v[104:107], v[156:159], v[192:195], v[104:107]
	v_mfma_f32_16x16x32_bf16 v[92:95], v[138:141], v[200:203], v[92:95]
	v_mfma_f32_16x16x32_bf16 v[88:91], v[156:159], v[200:203], v[88:91]
	v_mfma_f32_16x16x32_bf16 v[76:79], v[138:141], v[208:211], v[76:79]
	v_mfma_f32_16x16x32_bf16 v[72:75], v[156:159], v[208:211], v[72:75]
	v_mfma_f32_16x16x32_bf16 v[124:127], v[142:145], v[188:191], v[124:127]
	v_mfma_f32_16x16x32_bf16 v[120:123], v[164:167], v[188:191], v[120:123]
	v_mfma_f32_16x16x32_bf16 v[108:111], v[142:145], v[196:199], v[108:111]
	v_mfma_f32_16x16x32_bf16 v[104:107], v[164:167], v[196:199], v[104:107]
	v_mfma_f32_16x16x32_bf16 v[92:95], v[142:145], v[204:207], v[92:95]
	v_mfma_f32_16x16x32_bf16 v[88:91], v[164:167], v[204:207], v[88:91]
	v_mfma_f32_16x16x32_bf16 v[76:79], v[142:145], v[212:215], v[76:79]
	v_mfma_f32_16x16x32_bf16 v[72:75], v[164:167], v[212:215], v[72:75]
	s_setprio 0
	s_setprio 1
	v_mfma_f32_16x16x32_bf16 v[116:119], v[168:171], v[184:187], v[116:119]
	v_mfma_f32_16x16x32_bf16 v[112:115], v[176:179], v[184:187], v[112:115]
	v_mfma_f32_16x16x32_bf16 v[100:103], v[168:171], v[192:195], v[100:103]
	v_mfma_f32_16x16x32_bf16 v[96:99], v[176:179], v[192:195], v[96:99]
	v_mfma_f32_16x16x32_bf16 v[84:87], v[168:171], v[200:203], v[84:87]
	v_mfma_f32_16x16x32_bf16 v[80:83], v[176:179], v[200:203], v[80:83]
	v_mfma_f32_16x16x32_bf16 v[68:71], v[168:171], v[208:211], v[68:71]
	v_mfma_f32_16x16x32_bf16 v[64:67], v[176:179], v[208:211], v[64:67]
	v_mfma_f32_16x16x32_bf16 v[116:119], v[172:175], v[188:191], v[116:119]
	v_mfma_f32_16x16x32_bf16 v[112:115], v[180:183], v[188:191], v[112:115]
	v_mfma_f32_16x16x32_bf16 v[100:103], v[172:175], v[196:199], v[100:103]
	v_mfma_f32_16x16x32_bf16 v[96:99], v[180:183], v[196:199], v[96:99]
	s_setprio 2
	s_barrier
; #define PG8_STAGE(bufoff, gbase, voff) do { _Pragma("unroll") for (int _i = 0; _i < 2; ++_i) \
;         __builtin_amdgcn_global_load_lds((const unsigned*)((const char*)(gbase) + (voff)[_i]), (LAS unsigned*)(lds + (bufoff) + ldsw + _i * 8192), 16, 0, 0); } while (0)
; #define PG8_LDA(dst, b, h) do { _Pragma("unroll") for (int m = 0; m < 4; ++m) _Pragma("unroll") for (int k = 0; k < 2; ++k) dst[m][k] = *(const LAS bf16x8*)(lds + PG8_SA(b, h) + aoff + m * 2048 + k * 1024); } while (0)
; #define PG8_MMA(ai, bj, At, Bt) do { __builtin_amdgcn_s_setprio(1); _Pragma("unroll") for (int m = 0; m < 4; ++m) _Pragma("unroll") for (int n = 0; n < 2; ++n) _Pragma("unroll") for (int k = 0; k < 2; ++k) \
;         acc[ai][bj][m][n] = __builtin_amdgcn_mfma_f32_16x16x32_bf16(Bt[n][k], At[m][k], acc[ai][bj][m][n], 0, 0, 0); __builtin_amdgcn_s_setprio(0); } while (0)
; #define PG8_WAIT_V(n) asm volatile("s_waitcnt vmcnt(" #n ")" ::: "memory")
; #define PG8_WAIT_L(n) asm volatile("s_waitcnt lgkmcnt(" #n ")" ::: "memory")
; #define PG8_BAR __builtin_amdgcn_s_barrier()
; #define PG8_SCHED __builtin_amdgcn_sched_barrier(0)
; template <class Epi, class Sched>
; __device__ __forceinline__ void gemm_phase(LAS unsigned char* lds, const Gemm g, Sched S, const Epi& E) {
;     ...
;             PG8_WAIT_V(8); PG8_WAIT_L(0); PG8_BAR; PG8_MMA(0, 0, At, B0); PG8_MMA(0, 1, At, B1); PG8_BAR; PG8_SCHED;
;             PG8_LDA(At, 1, 1); PG8_STAGE(PG8_SB(1, 0), b3, voffB); PG8_STAGE(PG8_SB(1, 1), b3 + hstepB, voffB); PG8_STAGE(PG8_SA(1, 0), a3, voffA);
;             PG8_WAIT_V(8); PG8_WAIT_L(0); PG8_BAR; PG8_MMA(1, 0, At, B0); PG8_MMA(1, 1, At, B1); PG8_BAR; PG8_SCHED;
;         }
;         if (wr == 0) PG8_BAR;
	v_mfma_f32_16x16x32_bf16 v[84:87], v[172:175], v[204:207], v[84:87]
	v_mfma_f32_16x16x32_bf16 v[80:83], v[180:183], v[204:207], v[80:83]
	v_mfma_f32_16x16x32_bf16 v[68:71], v[172:175], v[212:215], v[68:71]
	v_mfma_f32_16x16x32_bf16 v[64:67], v[180:183], v[212:215], v[64:67]
	s_setprio 0
	s_add_i32 s24, s58, s29
	v_lshl_add_u64 v[146:147], v[146:147], 0, s[8:9]
	s_mov_b32 m0, s24
	ds_read_b128 v[184:187], v154 offset:49152
	ds_read_b128 v[188:191], v154 offset:50176
	ds_read_b128 v[192:195], v154 offset:51200
	ds_read_b128 v[196:199], v154 offset:52224
	ds_read_b128 v[200:203], v154 offset:53248
	ds_read_b128 v[204:207], v154 offset:54272
	ds_read_b128 v[208:211], v154 offset:55296
	ds_read_b128 v[212:215], v154 offset:56320
	global_load_lds_dwordx4 v[146:147], off
	s_add_i32 m0, s24, 0x2000
	s_add_u32 s22, s22, 0x40080
	v_lshl_add_u64 v[146:147], v[160:161], 0, s[8:9]
	s_addc_u32 s23, s23, 0
	s_add_i32 s24, s59, s29
	global_load_lds_dwordx4 v[146:147], off
	v_lshl_add_u64 v[146:147], s[22:23], 0, v[130:131]
	s_mov_b32 m0, s24
	s_nop 0
	global_load_lds_dwordx4 v[146:147], off
	v_lshl_add_u64 v[146:147], s[22:23], 0, v[128:129]
	s_add_i32 m0, s24, 0x2000
	s_nop 0
	global_load_lds_dwordx4 v[146:147], off
	v_lshl_add_u64 v[146:147], v[216:217], 0, s[8:9]
	s_mov_b32 m0, s40
	s_nop 0
	global_load_lds_dwordx4 v[146:147], off
	v_lshl_add_u64 v[146:147], v[218:219], 0, s[8:9]
	s_mov_b32 m0, s41
	s_nop 0
	global_load_lds_dwordx4 v[146:147], off
	s_waitcnt vmcnt(8)
	s_waitcnt lgkmcnt(0)
	s_barrier
	s_setprio 1
	s_waitcnt lgkmcnt(0)
	v_mfma_f32_16x16x32_bf16 v[60:63], v[138:141], v[184:187], v[60:63]
	v_mfma_f32_16x16x32_bf16 v[56:59], v[156:159], v[184:187], v[56:59]
	v_mfma_f32_16x16x32_bf16 v[44:47], v[138:141], v[192:195], v[44:47]
	v_mfma_f32_16x16x32_bf16 v[40:43], v[156:159], v[192:195], v[40:43]
	v_mfma_f32_16x16x32_bf16 v[28:31], v[138:141], v[200:203], v[28:31]
	v_mfma_f32_16x16x32_bf16 v[24:27], v[156:159], v[200:203], v[24:27]
	v_mfma_f32_16x16x32_bf16 v[12:15], v[138:141], v[208:211], v[12:15]
	v_mfma_f32_16x16x32_bf16 v[8:11], v[156:159], v[208:211], v[8:11]
	v_mfma_f32_16x16x32_bf16 v[60:63], v[142:145], v[188:191], v[60:63]
	v_mfma_f32_16x16x32_bf16 v[56:59], v[164:167], v[188:191], v[56:59]
	v_mfma_f32_16x16x32_bf16 v[44:47], v[142:145], v[196:199], v[44:47]
	v_mfma_f32_16x16x32_bf16 v[40:43], v[164:167], v[196:199], v[40:43]
	v_mfma_f32_16x16x32_bf16 v[28:31], v[142:145], v[204:207], v[28:31]
	v_mfma_f32_16x16x32_bf16 v[24:27], v[164:167], v[204:207], v[24:27]
	v_mfma_f32_16x16x32_bf16 v[12:15], v[142:145], v[212:215], v[12:15]
	v_mfma_f32_16x16x32_bf16 v[8:11], v[164:167], v[212:215], v[8:11]
	s_setprio 0
	s_setprio 1
	v_mfma_f32_16x16x32_bf16 v[52:55], v[168:171], v[184:187], v[52:55]
	v_mfma_f32_16x16x32_bf16 v[48:51], v[176:179], v[184:187], v[48:51]
	v_mfma_f32_16x16x32_bf16 v[36:39], v[168:171], v[192:195], v[36:39]
	v_mfma_f32_16x16x32_bf16 v[32:35], v[176:179], v[192:195], v[32:35]
	v_mfma_f32_16x16x32_bf16 v[20:23], v[168:171], v[200:203], v[20:23]
	v_mfma_f32_16x16x32_bf16 v[16:19], v[176:179], v[200:203], v[16:19]
	v_mfma_f32_16x16x32_bf16 v[4:7], v[168:171], v[208:211], v[4:7]
	v_mfma_f32_16x16x32_bf16 v[0:3], v[176:179], v[208:211], v[0:3]
	v_mfma_f32_16x16x32_bf16 v[52:55], v[172:175], v[188:191], v[52:55]
	v_mfma_f32_16x16x32_bf16 v[48:51], v[180:183], v[188:191], v[48:51]
	v_mfma_f32_16x16x32_bf16 v[36:39], v[172:175], v[196:199], v[36:39]
	v_mfma_f32_16x16x32_bf16 v[32:35], v[180:183], v[196:199], v[32:35]
	s_setprio 2
	s_barrier
	v_mfma_f32_16x16x32_bf16 v[20:23], v[172:175], v[204:207], v[20:23]
	v_mfma_f32_16x16x32_bf16 v[16:19], v[180:183], v[204:207], v[16:19]
	v_mfma_f32_16x16x32_bf16 v[4:7], v[172:175], v[212:215], v[4:7]
	v_mfma_f32_16x16x32_bf16 v[0:3], v[180:183], v[212:215], v[0:3]
	s_setprio 0
	s_add_i32 s57, s57, 2
	s_add_u32 s20, s20, 0x100
	s_addc_u32 s21, s21, 0
	s_add_u32 s55, s55, 0x100
	s_addc_u32 s56, s56, 0
	s_cmp_gt_u32 s57, 13
	s_cbranch_scc0 .LBB0_199
	s_and_b64 vcc, exec, s[12:13]
	s_cbranch_vccz .LBB0_202
	s_barrier

; #define PG8_STAGE(bufoff, gbase, voff) do { _Pragma("unroll") for (int _i = 0; _i < 2; ++_i) \
;         __builtin_amdgcn_global_load_lds((const unsigned*)((const char*)(gbase) + (voff)[_i]), (LAS unsigned*)(lds + (bufoff) + ldsw + _i * 8192), 16, 0, 0); } while (0)
; #define PG8_LDA(dst, b, h) do { _Pragma("unroll") for (int m = 0; m < 4; ++m) _Pragma("unroll") for (int k = 0; k < 2; ++k) dst[m][k] = *(const LAS bf16x8*)(lds + PG8_SA(b, h) + aoff + m * 2048 + k * 1024); } while (0)
; #define PG8_LDB(dst, b, h) do { _Pragma("unroll") for (int n = 0; n < 2; ++n) _Pragma("unroll") for (int k = 0; k < 2; ++k) dst[n][k] = *(const LAS bf16x8*)(lds + PG8_SB(b, h) + boff + n * 2048 + k * 1024); } while (0)
; #define PG8_MMA(ai, bj, At, Bt) do { __builtin_amdgcn_s_setprio(1); _Pragma("unroll") for (int m = 0; m < 4; ++m) _Pragma("unroll") for (int n = 0; n < 2; ++n) _Pragma("unroll") for (int k = 0; k < 2; ++k) \
;         acc[ai][bj][m][n] = __builtin_amdgcn_mfma_f32_16x16x32_bf16(Bt[n][k], At[m][k], acc[ai][bj][m][n], 0, 0, 0); __builtin_amdgcn_s_setprio(0); } while (0)
; #define PG8_WAIT_V(n) asm volatile("s_waitcnt vmcnt(" #n ")" ::: "memory")
; #define PG8_WAIT_L(n) asm volatile("s_waitcnt lgkmcnt(" #n ")" ::: "memory")
; #define PG8_BAR __builtin_amdgcn_s_barrier()
; template <class Epi, class Sched>
; __device__ __forceinline__ void gemm_phase(LAS unsigned char* lds, const Gemm g, Sched S, const Epi& E) {
;     ...
;         const bool has_next = S.next(ui + 1, nxt);
;         const char* nA = has_next ? (const char*)g.A + a_off(g, nxt) : cA; const char* nB = has_next ? (const char*)g.Bt + b_off(g, nxt) : cB;
;         for (int t = 0; t < nt; t += 2) {
;             const bool last = (t == nt - 2);
;             const char* a1 = cA + (size_t)(t + 1) * kstep;
;             const char* a2 = last ? nA : cA + (size_t)(t + 2) * kstep; const char* b2 = last ? nB : cB + (size_t)(t + 2) * kstep;
;             const char* a3 = a2 + kstep; const char* b3 = b2 + kstep;
;             PG8_LDB(B0, 0, 0); PG8_LDB(B1, 0, 1); PG8_SCHED; PG8_LDA(At, 0, 0); PG8_STAGE(PG8_SA(1, 1), a1 + hstepA, voffA);
;             PG8_WAIT_V(8); PG8_WAIT_L(0); PG8_BAR; PG8_MMA(0, 0, At, B0); PG8_MMA(0, 1, At, B1); PG8_BAR; PG8_SCHED;
;             PG8_LDA(At, 0, 1); PG8_STAGE(PG8_SB(0, 0), b2, voffB); PG8_STAGE(PG8_SB(0, 1), b2 + hstepB, voffB); PG8_STAGE(PG8_SA(0, 0), a2, voffA);
.LBB0_514:
	s_cmp_lt_i32 s98, s20
	s_cselect_b64 s[90:91], -1, 0
	s_lshl_b32 s2, s41, 3
	s_and_b32 s3, s73, 7
	s_or_b32 s30, s3, s2
	s_ashr_i32 s34, s73, 3
	s_ashr_i32 s31, s30, 31
	s_ashr_i32 s35, s34, 31
	s_lshl_b64 s[2:3], s[30:31], 19
	s_lshl_b64 s[18:19], s[34:35], 9
	s_add_u32 s31, s16, s18
	s_addc_u32 s35, s17, s19
	s_add_u32 s88, s31, s2
	s_addc_u32 s89, s35, s3
	s_and_b64 s[2:3], s[90:91], exec
	s_cselect_b32 s67, s89, s11
	s_cselect_b32 s66, s88, s10
	s_ashr_i32 s2, s41, 1
	s_ashr_i32 s3, s2, 31
	s_lshl_b64 s[2:3], s[2:3], 19
	s_add_u32 s2, s76, s2
	s_addc_u32 s3, s77, s3
	s_add_u32 s92, s2, s18
	s_addc_u32 s93, s3, s19
	s_and_b64 s[2:3], s[90:91], exec
	s_cselect_b32 s53, s93, s55
	s_cselect_b32 s52, s92, s54
	s_add_i32 s40, 0, 0x10000
	s_add_i32 s31, 0, 0x14000
	v_add_u32_e32 v190, s40, v149
	v_add_u32_e32 v191, s31, v149
	ds_read_b128 v[2:5], v190
	ds_read_b128 v[6:9], v190 offset:1024
	ds_read_b128 v[10:13], v190 offset:2048
	ds_read_b128 v[14:17], v190 offset:3072
	ds_read_b128 v[18:21], v191
	ds_read_b128 v[22:25], v191 offset:1024
	ds_read_b128 v[26:29], v191 offset:2048
	ds_read_b128 v[30:33], v191 offset:3072
	s_add_u32 s2, s10, 0x40080
	s_addc_u32 s3, s11, 0
	s_add_i32 s59, s43, 0xc000
	v_lshl_add_u64 v[66:67], s[2:3], 0, v[134:135]
	s_mov_b32 m0, s59
	s_add_i32 s18, s43, 0xe000
	ds_read_b128 v[34:37], v153
	ds_read_b128 v[38:41], v153 offset:1024
	ds_read_b128 v[42:45], v153 offset:2048
	ds_read_b128 v[46:49], v153 offset:3072
	ds_read_b128 v[50:53], v153 offset:4096
	ds_read_b128 v[54:57], v153 offset:5120
	ds_read_b128 v[58:61], v153 offset:6144
	ds_read_b128 v[62:65], v153 offset:7168
	global_load_lds_dwordx4 v[66:67], off
	v_lshl_add_u64 v[66:67], s[2:3], 0, v[132:133]
	s_mov_b32 m0, s18
	s_nop 0
	global_load_lds_dwordx4 v[66:67], off
	s_waitcnt vmcnt(8)
	s_waitcnt lgkmcnt(0)
	s_barrier
	s_setprio 1
	s_waitcnt lgkmcnt(0)
	v_mfma_f32_16x16x32_bf16 v[66:69], v[2:5], v[34:37], 0
	v_mfma_f32_16x16x32_bf16 v[70:73], v[10:13], v[34:37], 0
	v_mfma_f32_16x16x32_bf16 v[74:77], v[2:5], v[42:45], 0
	v_mfma_f32_16x16x32_bf16 v[78:81], v[10:13], v[42:45], 0
	v_mfma_f32_16x16x32_bf16 v[82:85], v[2:5], v[50:53], 0
	v_mfma_f32_16x16x32_bf16 v[86:89], v[10:13], v[50:53], 0
	v_mfma_f32_16x16x32_bf16 v[90:93], v[2:5], v[58:61], 0
	v_mfma_f32_16x16x32_bf16 v[94:97], v[10:13], v[58:61], 0
	v_mfma_f32_16x16x32_bf16 v[66:69], v[6:9], v[38:41], v[66:69]
	v_mfma_f32_16x16x32_bf16 v[70:73], v[14:17], v[38:41], v[70:73]
	v_mfma_f32_16x16x32_bf16 v[74:77], v[6:9], v[46:49], v[74:77]
	v_mfma_f32_16x16x32_bf16 v[78:81], v[14:17], v[46:49], v[78:81]
	v_mfma_f32_16x16x32_bf16 v[82:85], v[6:9], v[54:57], v[82:85]
	v_mfma_f32_16x16x32_bf16 v[86:89], v[14:17], v[54:57], v[86:89]
	v_mfma_f32_16x16x32_bf16 v[90:93], v[6:9], v[62:65], v[90:93]
	v_mfma_f32_16x16x32_bf16 v[94:97], v[14:17], v[62:65], v[94:97]
	s_setprio 0
	s_setprio 1
	v_mfma_f32_16x16x32_bf16 v[98:101], v[18:21], v[34:37], 0
	v_mfma_f32_16x16x32_bf16 v[34:37], v[26:29], v[34:37], 0
	v_mfma_f32_16x16x32_bf16 v[98:101], v[22:25], v[38:41], v[98:101]
	v_mfma_f32_16x16x32_bf16 v[34:37], v[30:33], v[38:41], v[34:37]
	v_mfma_f32_16x16x32_bf16 v[38:41], v[18:21], v[42:45], 0
	v_mfma_f32_16x16x32_bf16 v[42:45], v[26:29], v[42:45], 0
	v_mfma_f32_16x16x32_bf16 v[38:41], v[22:25], v[46:49], v[38:41]
	v_mfma_f32_16x16x32_bf16 v[42:45], v[30:33], v[46:49], v[42:45]
	v_mfma_f32_16x16x32_bf16 v[46:49], v[18:21], v[50:53], 0
	v_mfma_f32_16x16x32_bf16 v[50:53], v[26:29], v[50:53], 0
	v_mfma_f32_16x16x32_bf16 v[46:49], v[22:25], v[54:57], v[46:49]
	v_mfma_f32_16x16x32_bf16 v[50:53], v[30:33], v[54:57], v[50:53]
	s_setprio 2
	s_barrier
	v_mfma_f32_16x16x32_bf16 v[54:57], v[18:21], v[58:61], 0
	v_mfma_f32_16x16x32_bf16 v[58:61], v[26:29], v[58:61], 0
	v_mfma_f32_16x16x32_bf16 v[54:57], v[22:25], v[62:65], v[54:57]
	v_mfma_f32_16x16x32_bf16 v[58:61], v[30:33], v[62:65], v[58:61]
	s_setprio 0
	s_add_i32 s40, s40, s56
	v_lshl_add_u64 v[216:217], s[54:55], 0, v[0:1]
	s_add_i32 s19, s40, 0x2000
	v_lshl_add_u64 v[136:137], v[216:217], 0, s[78:79]
	s_mov_b32 m0, s40
	v_lshl_add_u64 v[218:219], s[54:55], 0, v[130:131]
	s_add_u32 s2, s54, 0x40100
	ds_read_b128 v[62:65], v153 offset:16384
	ds_read_b128 v[102:105], v153 offset:17408
	ds_read_b128 v[106:109], v153 offset:18432
	ds_read_b128 v[110:113], v153 offset:19456
	ds_read_b128 v[114:117], v153 offset:20480
	ds_read_b128 v[118:121], v153 offset:21504
	ds_read_b128 v[122:125], v153 offset:22528
	ds_read_b128 v[126:129], v153 offset:23552
	global_load_lds_dwordx4 v[136:137], off
	v_lshl_add_u64 v[136:137], v[218:219], 0, s[78:79]
	s_mov_b32 m0, s19
	s_addc_u32 s3, s55, 0
	s_add_i32 s31, s31, s56
	global_load_lds_dwordx4 v[136:137], off
	v_lshl_add_u64 v[136:137], s[2:3], 0, v[0:1]
	s_mov_b32 m0, s31
	s_add_i32 s35, s31, 0x2000
	global_load_lds_dwordx4 v[136:137], off
	v_lshl_add_u64 v[136:137], s[2:3], 0, v[130:131]
	s_mov_b32 m0, s35
	v_lshl_add_u64 v[220:221], s[10:11], 0, v[134:135]
	global_load_lds_dwordx4 v[136:137], off
	v_lshl_add_u64 v[136:137], v[220:221], 0, s[78:79]
	s_mov_b32 m0, s43
	v_lshl_add_u64 v[222:223], s[10:11], 0, v[132:133]
	global_load_lds_dwordx4 v[136:137], off
	v_lshl_add_u64 v[136:137], v[222:223], 0, s[78:79]
	s_mov_b32 m0, s45
	s_nop 0
	global_load_lds_dwordx4 v[136:137], off
	s_waitcnt vmcnt(8)
	s_waitcnt lgkmcnt(0)
	s_barrier
; #define PG8_STAGE(bufoff, gbase, voff) do { _Pragma("unroll") for (int _i = 0; _i < 2; ++_i) \
;         __builtin_amdgcn_global_load_lds((const unsigned*)((const char*)(gbase) + (voff)[_i]), (LAS unsigned*)(lds + (bufoff) + ldsw + _i * 8192), 16, 0, 0); } while (0)
; #define PG8_LDA(dst, b, h) do { _Pragma("unroll") for (int m = 0; m < 4; ++m) _Pragma("unroll") for (int k = 0; k < 2; ++k) dst[m][k] = *(const LAS bf16x8*)(lds + PG8_SA(b, h) + aoff + m * 2048 + k * 1024); } while (0)
; #define PG8_LDB(dst, b, h) do { _Pragma("unroll") for (int n = 0; n < 2; ++n) _Pragma("unroll") for (int k = 0; k < 2; ++k) dst[n][k] = *(const LAS bf16x8*)(lds + PG8_SB(b, h) + boff + n * 2048 + k * 1024); } while (0)
; #define PG8_MMA(ai, bj, At, Bt) do { __builtin_amdgcn_s_setprio(1); _Pragma("unroll") for (int m = 0; m < 4; ++m) _Pragma("unroll") for (int n = 0; n < 2; ++n) _Pragma("unroll") for (int k = 0; k < 2; ++k) \
;         acc[ai][bj][m][n] = __builtin_amdgcn_mfma_f32_16x16x32_bf16(Bt[n][k], At[m][k], acc[ai][bj][m][n], 0, 0, 0); __builtin_amdgcn_s_setprio(0); } while (0)
; #define PG8_WAIT_V(n) asm volatile("s_waitcnt vmcnt(" #n ")" ::: "memory")
; #define PG8_WAIT_L(n) asm volatile("s_waitcnt lgkmcnt(" #n ")" ::: "memory")
; #define PG8_BAR __builtin_amdgcn_s_barrier()
; #define PG8_SCHED __builtin_amdgcn_sched_barrier(0)
; template <class Epi, class Sched>
; __device__ __forceinline__ void gemm_phase(LAS unsigned char* lds, const Gemm g, Sched S, const Epi& E) {
;     ...
;             PG8_WAIT_V(8); PG8_WAIT_L(0); PG8_BAR; PG8_MMA(1, 0, At, B0); PG8_MMA(1, 1, At, B1); PG8_BAR; PG8_SCHED;
;             PG8_LDB(B0, 1, 0); PG8_LDB(B1, 1, 1); PG8_SCHED; PG8_LDA(At, 1, 0); PG8_STAGE(PG8_SA(0, 1), a2 + hstepA, voffA);
;             PG8_WAIT_V(8); PG8_WAIT_L(0); PG8_BAR; PG8_MMA(0, 0, At, B0); PG8_MMA(0, 1, At, B1); PG8_BAR; PG8_SCHED;
	s_setprio 1
	s_waitcnt lgkmcnt(0)
	v_mfma_f32_16x16x32_bf16 v[136:139], v[2:5], v[62:65], 0
	v_mfma_f32_16x16x32_bf16 v[144:147], v[2:5], v[106:109], 0
	v_mfma_f32_16x16x32_bf16 v[158:161], v[2:5], v[114:117], 0
	v_mfma_f32_16x16x32_bf16 v[2:5], v[2:5], v[122:125], 0
	v_mfma_f32_16x16x32_bf16 v[136:139], v[6:9], v[102:105], v[136:139]
	v_mfma_f32_16x16x32_bf16 v[144:147], v[6:9], v[110:113], v[144:147]
	v_mfma_f32_16x16x32_bf16 v[158:161], v[6:9], v[118:121], v[158:161]
	v_mfma_f32_16x16x32_bf16 v[2:5], v[6:9], v[126:129], v[2:5]
	v_mfma_f32_16x16x32_bf16 v[6:9], v[10:13], v[122:125], 0
	v_mfma_f32_16x16x32_bf16 v[140:143], v[10:13], v[62:65], 0
	v_mfma_f32_16x16x32_bf16 v[154:157], v[10:13], v[106:109], 0
	v_mfma_f32_16x16x32_bf16 v[164:167], v[10:13], v[114:117], 0
	v_mfma_f32_16x16x32_bf16 v[6:9], v[14:17], v[126:129], v[6:9]
	v_mfma_f32_16x16x32_bf16 v[140:143], v[14:17], v[102:105], v[140:143]
	v_mfma_f32_16x16x32_bf16 v[154:157], v[14:17], v[110:113], v[154:157]
	v_mfma_f32_16x16x32_bf16 v[164:167], v[14:17], v[118:121], v[164:167]
	s_setprio 0
	s_setprio 1
	v_mfma_f32_16x16x32_bf16 v[10:13], v[18:21], v[62:65], 0
	v_mfma_f32_16x16x32_bf16 v[14:17], v[26:29], v[62:65], 0
	v_mfma_f32_16x16x32_bf16 v[10:13], v[22:25], v[102:105], v[10:13]
	v_mfma_f32_16x16x32_bf16 v[14:17], v[30:33], v[102:105], v[14:17]
	v_mfma_f32_16x16x32_bf16 v[62:65], v[18:21], v[106:109], 0
	v_mfma_f32_16x16x32_bf16 v[102:105], v[26:29], v[106:109], 0
	v_mfma_f32_16x16x32_bf16 v[106:109], v[18:21], v[114:117], 0
	v_mfma_f32_16x16x32_bf16 v[18:21], v[18:21], v[122:125], 0
	v_mfma_f32_16x16x32_bf16 v[62:65], v[22:25], v[110:113], v[62:65]
	v_mfma_f32_16x16x32_bf16 v[102:105], v[30:33], v[110:113], v[102:105]
	v_mfma_f32_16x16x32_bf16 v[106:109], v[22:25], v[118:121], v[106:109]
	v_mfma_f32_16x16x32_bf16 v[110:113], v[26:29], v[114:117], 0
	s_setprio 2
	s_barrier
	v_mfma_f32_16x16x32_bf16 v[18:21], v[22:25], v[126:129], v[18:21]
	v_mfma_f32_16x16x32_bf16 v[22:25], v[26:29], v[122:125], 0
	v_mfma_f32_16x16x32_bf16 v[110:113], v[30:33], v[118:121], v[110:113]
	v_mfma_f32_16x16x32_bf16 v[22:25], v[30:33], v[126:129], v[22:25]
	s_setprio 0
	s_add_i32 s60, 0, 0x18000
	s_add_i32 s61, 0, 0x1c000
	v_add_u32_e32 v226, s60, v149
	v_add_u32_e32 v227, s61, v149
	ds_read_b128 v[26:29], v226
	ds_read_b128 v[30:33], v226 offset:1024
	ds_read_b128 v[114:117], v226 offset:2048
	ds_read_b128 v[118:121], v226 offset:3072
	ds_read_b128 v[122:125], v227
	ds_read_b128 v[126:129], v227 offset:1024
	ds_read_b128 v[168:171], v227 offset:2048
	ds_read_b128 v[172:175], v227 offset:3072
	s_add_u32 s2, s10, 0x40100
	s_addc_u32 s3, s11, 0
	s_mov_b32 m0, s84
	v_lshl_add_u64 v[224:225], s[2:3], 0, v[134:135]
	ds_read_b128 v[176:179], v153 offset:32768
	ds_read_b128 v[180:183], v153 offset:33792
	ds_read_b128 v[192:195], v153 offset:34816
	ds_read_b128 v[196:199], v153 offset:35840
	ds_read_b128 v[200:203], v153 offset:36864
	ds_read_b128 v[204:207], v153 offset:37888
	ds_read_b128 v[208:211], v153 offset:38912
	ds_read_b128 v[212:215], v153 offset:39936
	global_load_lds_dwordx4 v[224:225], off
	v_lshl_add_u64 v[224:225], s[2:3], 0, v[132:133]
	s_mov_b32 m0, s94
	s_nop 0
	global_load_lds_dwordx4 v[224:225], off
	s_waitcnt vmcnt(8)
	s_waitcnt lgkmcnt(0)
	s_barrier
	s_setprio 1
	s_waitcnt lgkmcnt(0)
	v_mfma_f32_16x16x32_bf16 v[66:69], v[26:29], v[176:179], v[66:69]
	v_mfma_f32_16x16x32_bf16 v[70:73], v[114:117], v[176:179], v[70:73]
	v_mfma_f32_16x16x32_bf16 v[74:77], v[26:29], v[192:195], v[74:77]
	v_mfma_f32_16x16x32_bf16 v[78:81], v[114:117], v[192:195], v[78:81]
	v_mfma_f32_16x16x32_bf16 v[82:85], v[26:29], v[200:203], v[82:85]
	v_mfma_f32_16x16x32_bf16 v[86:89], v[114:117], v[200:203], v[86:89]
	v_mfma_f32_16x16x32_bf16 v[90:93], v[26:29], v[208:211], v[90:93]
	v_mfma_f32_16x16x32_bf16 v[94:97], v[114:117], v[208:211], v[94:97]
	v_mfma_f32_16x16x32_bf16 v[66:69], v[30:33], v[180:183], v[66:69]
	v_mfma_f32_16x16x32_bf16 v[70:73], v[118:121], v[180:183], v[70:73]
	v_mfma_f32_16x16x32_bf16 v[74:77], v[30:33], v[196:199], v[74:77]
	v_mfma_f32_16x16x32_bf16 v[78:81], v[118:121], v[196:199], v[78:81]
	v_mfma_f32_16x16x32_bf16 v[82:85], v[30:33], v[204:207], v[82:85]
	v_mfma_f32_16x16x32_bf16 v[86:89], v[118:121], v[204:207], v[86:89]
	v_mfma_f32_16x16x32_bf16 v[90:93], v[30:33], v[212:215], v[90:93]
	v_mfma_f32_16x16x32_bf16 v[94:97], v[118:121], v[212:215], v[94:97]
	s_setprio 0
	s_setprio 1
	v_mfma_f32_16x16x32_bf16 v[98:101], v[122:125], v[176:179], v[98:101]
	v_mfma_f32_16x16x32_bf16 v[34:37], v[168:171], v[176:179], v[34:37]
	v_mfma_f32_16x16x32_bf16 v[38:41], v[122:125], v[192:195], v[38:41]
	v_mfma_f32_16x16x32_bf16 v[42:45], v[168:171], v[192:195], v[42:45]
	v_mfma_f32_16x16x32_bf16 v[46:49], v[122:125], v[200:203], v[46:49]
	v_mfma_f32_16x16x32_bf16 v[50:53], v[168:171], v[200:203], v[50:53]
	v_mfma_f32_16x16x32_bf16 v[54:57], v[122:125], v[208:211], v[54:57]
	v_mfma_f32_16x16x32_bf16 v[58:61], v[168:171], v[208:211], v[58:61]
	v_mfma_f32_16x16x32_bf16 v[98:101], v[126:129], v[180:183], v[98:101]
	v_mfma_f32_16x16x32_bf16 v[34:37], v[172:175], v[180:183], v[34:37]
	v_mfma_f32_16x16x32_bf16 v[38:41], v[126:129], v[196:199], v[38:41]
	v_mfma_f32_16x16x32_bf16 v[42:45], v[172:175], v[196:199], v[42:45]
	s_setprio 2
	s_barrier
; #define PG8_STAGE(bufoff, gbase, voff) do { _Pragma("unroll") for (int _i = 0; _i < 2; ++_i) \
;         __builtin_amdgcn_global_load_lds((const unsigned*)((const char*)(gbase) + (voff)[_i]), (LAS unsigned*)(lds + (bufoff) + ldsw + _i * 8192), 16, 0, 0); } while (0)
; #define PG8_LDA(dst, b, h) do { _Pragma("unroll") for (int m = 0; m < 4; ++m) _Pragma("unroll") for (int k = 0; k < 2; ++k) dst[m][k] = *(const LAS bf16x8*)(lds + PG8_SA(b, h) + aoff + m * 2048 + k * 1024); } while (0)
; #define PG8_LDB(dst, b, h) do { _Pragma("unroll") for (int n = 0; n < 2; ++n) _Pragma("unroll") for (int k = 0; k < 2; ++k) dst[n][k] = *(const LAS bf16x8*)(lds + PG8_SB(b, h) + boff + n * 2048 + k * 1024); } while (0)
; #define PG8_MMA(ai, bj, At, Bt) do { __builtin_amdgcn_s_setprio(1); _Pragma("unroll") for (int m = 0; m < 4; ++m) _Pragma("unroll") for (int n = 0; n < 2; ++n) _Pragma("unroll") for (int k = 0; k < 2; ++k) \
;         acc[ai][bj][m][n] = __builtin_amdgcn_mfma_f32_16x16x32_bf16(Bt[n][k], At[m][k], acc[ai][bj][m][n], 0, 0, 0); __builtin_amdgcn_s_setprio(0); } while (0)
; #define PG8_WAIT_V(n) asm volatile("s_waitcnt vmcnt(" #n ")" ::: "memory")
; #define PG8_WAIT_L(n) asm volatile("s_waitcnt lgkmcnt(" #n ")" ::: "memory")
; #define PG8_BAR __builtin_amdgcn_s_barrier()
; #define PG8_SCHED __builtin_amdgcn_sched_barrier(0)
; template <class Epi, class Sched>
; __device__ __forceinline__ void gemm_phase(LAS unsigned char* lds, const Gemm g, Sched S, const Epi& E) {
;     ...
;             PG8_LDB(B0, 0, 0); PG8_LDB(B1, 0, 1); PG8_SCHED; PG8_LDA(At, 0, 0); PG8_STAGE(PG8_SA(1, 1), a1 + hstepA, voffA);
;     ...
;             PG8_WAIT_V(8); PG8_WAIT_L(0); PG8_BAR; PG8_MMA(0, 0, At, B0); PG8_MMA(0, 1, At, B1); PG8_BAR; PG8_SCHED;
;             PG8_LDA(At, 1, 1); PG8_STAGE(PG8_SB(1, 0), b3, voffB); PG8_STAGE(PG8_SB(1, 1), b3 + hstepB, voffB); PG8_STAGE(PG8_SA(1, 0), a3, voffA);
;             PG8_WAIT_V(8); PG8_WAIT_L(0); PG8_BAR; PG8_MMA(1, 0, At, B0); PG8_MMA(1, 1, At, B1); PG8_BAR; PG8_SCHED;
	v_mfma_f32_16x16x32_bf16 v[46:49], v[126:129], v[204:207], v[46:49]
	v_mfma_f32_16x16x32_bf16 v[50:53], v[172:175], v[204:207], v[50:53]
	v_mfma_f32_16x16x32_bf16 v[54:57], v[126:129], v[212:215], v[54:57]
	v_mfma_f32_16x16x32_bf16 v[58:61], v[172:175], v[212:215], v[58:61]
	s_setprio 0
	s_add_i32 s60, s60, s56
	s_mov_b64 s[62:63], 0x180
	s_add_i32 s58, s60, 0x2000
	v_lshl_add_u64 v[216:217], v[216:217], 0, s[62:63]
	s_mov_b32 m0, s60
	s_add_u32 s2, s54, 0x40180
	ds_read_b128 v[176:179], v153 offset:49152
	ds_read_b128 v[180:183], v153 offset:50176
	ds_read_b128 v[192:195], v153 offset:51200
	ds_read_b128 v[196:199], v153 offset:52224
	ds_read_b128 v[200:203], v153 offset:53248
	ds_read_b128 v[204:207], v153 offset:54272
	ds_read_b128 v[208:211], v153 offset:55296
	ds_read_b128 v[212:215], v153 offset:56320
	global_load_lds_dwordx4 v[216:217], off
	v_lshl_add_u64 v[216:217], v[218:219], 0, s[62:63]
	s_mov_b32 m0, s58
	s_addc_u32 s3, s55, 0
	s_add_i32 s54, s61, s56
	global_load_lds_dwordx4 v[216:217], off
	v_lshl_add_u64 v[216:217], s[2:3], 0, v[0:1]
	s_mov_b32 m0, s54
	s_add_i32 s55, s54, 0x2000
	global_load_lds_dwordx4 v[216:217], off
	v_lshl_add_u64 v[216:217], s[2:3], 0, v[130:131]
	s_mov_b32 m0, s55
	s_nop 0
	global_load_lds_dwordx4 v[216:217], off
	v_lshl_add_u64 v[216:217], v[220:221], 0, s[62:63]
	s_mov_b32 m0, s96
	s_nop 0
	global_load_lds_dwordx4 v[216:217], off
	v_lshl_add_u64 v[216:217], v[222:223], 0, s[62:63]
	s_mov_b32 m0, s97
	s_nop 0
	global_load_lds_dwordx4 v[216:217], off
	s_waitcnt vmcnt(8)
	s_waitcnt lgkmcnt(0)
	s_barrier
	s_setprio 1
	s_waitcnt lgkmcnt(0)
	v_mfma_f32_16x16x32_bf16 v[2:5], v[26:29], v[208:211], v[2:5]
	v_mfma_f32_16x16x32_bf16 v[6:9], v[114:117], v[208:211], v[6:9]
	v_mfma_f32_16x16x32_bf16 v[136:139], v[26:29], v[176:179], v[136:139]
	v_mfma_f32_16x16x32_bf16 v[140:143], v[114:117], v[176:179], v[140:143]
	v_mfma_f32_16x16x32_bf16 v[144:147], v[26:29], v[192:195], v[144:147]
	v_mfma_f32_16x16x32_bf16 v[154:157], v[114:117], v[192:195], v[154:157]
	v_mfma_f32_16x16x32_bf16 v[158:161], v[26:29], v[200:203], v[158:161]
	v_mfma_f32_16x16x32_bf16 v[164:167], v[114:117], v[200:203], v[164:167]
	v_mfma_f32_16x16x32_bf16 v[2:5], v[30:33], v[212:215], v[2:5]
	v_mfma_f32_16x16x32_bf16 v[6:9], v[118:121], v[212:215], v[6:9]
	v_mfma_f32_16x16x32_bf16 v[136:139], v[30:33], v[180:183], v[136:139]
	v_mfma_f32_16x16x32_bf16 v[140:143], v[118:121], v[180:183], v[140:143]
	v_mfma_f32_16x16x32_bf16 v[144:147], v[30:33], v[196:199], v[144:147]
	v_mfma_f32_16x16x32_bf16 v[154:157], v[118:121], v[196:199], v[154:157]
	v_mfma_f32_16x16x32_bf16 v[158:161], v[30:33], v[204:207], v[158:161]
	v_mfma_f32_16x16x32_bf16 v[164:167], v[118:121], v[204:207], v[164:167]
	s_setprio 0
	s_setprio 1
	v_mfma_f32_16x16x32_bf16 v[10:13], v[122:125], v[176:179], v[10:13]
	v_mfma_f32_16x16x32_bf16 v[14:17], v[168:171], v[176:179], v[14:17]
	v_mfma_f32_16x16x32_bf16 v[26:29], v[122:125], v[192:195], v[62:65]
	v_mfma_f32_16x16x32_bf16 v[30:33], v[168:171], v[192:195], v[102:105]
	v_mfma_f32_16x16x32_bf16 v[62:65], v[122:125], v[200:203], v[106:109]
	v_mfma_f32_16x16x32_bf16 v[102:105], v[168:171], v[200:203], v[110:113]
	v_mfma_f32_16x16x32_bf16 v[18:21], v[122:125], v[208:211], v[18:21]
	v_mfma_f32_16x16x32_bf16 v[22:25], v[168:171], v[208:211], v[22:25]
	v_mfma_f32_16x16x32_bf16 v[10:13], v[126:129], v[180:183], v[10:13]
	v_mfma_f32_16x16x32_bf16 v[14:17], v[172:175], v[180:183], v[14:17]
	v_mfma_f32_16x16x32_bf16 v[26:29], v[126:129], v[196:199], v[26:29]
	v_mfma_f32_16x16x32_bf16 v[30:33], v[172:175], v[196:199], v[30:33]
	s_setprio 2
	s_barrier
	v_mfma_f32_16x16x32_bf16 v[62:65], v[126:129], v[204:207], v[62:65]
	v_mfma_f32_16x16x32_bf16 v[102:105], v[172:175], v[204:207], v[102:105]
	v_mfma_f32_16x16x32_bf16 v[18:21], v[126:129], v[212:215], v[18:21]
	v_mfma_f32_16x16x32_bf16 v[22:25], v[172:175], v[212:215], v[22:25]
	s_setprio 0
	ds_read_b128 v[106:109], v190
	ds_read_b128 v[110:113], v190 offset:1024
	ds_read_b128 v[114:117], v190 offset:2048
	ds_read_b128 v[118:121], v190 offset:3072
	ds_read_b128 v[122:125], v191
	ds_read_b128 v[126:129], v191 offset:1024
	ds_read_b128 v[168:171], v191 offset:2048
	ds_read_b128 v[172:175], v191 offset:3072
	s_add_u32 s2, s10, 0x40180
	s_addc_u32 s3, s11, 0
	s_mov_b32 m0, s59
	v_lshl_add_u64 v[216:217], s[2:3], 0, v[134:135]
	ds_read_b128 v[176:179], v153
	ds_read_b128 v[180:183], v153 offset:1024
	ds_read_b128 v[192:195], v153 offset:2048
	ds_read_b128 v[196:199], v153 offset:3072
	ds_read_b128 v[200:203], v153 offset:4096
	ds_read_b128 v[204:207], v153 offset:5120
	ds_read_b128 v[208:211], v153 offset:6144
	ds_read_b128 v[212:215], v153 offset:7168
	global_load_lds_dwordx4 v[216:217], off
	v_lshl_add_u64 v[216:217], s[2:3], 0, v[132:133]
	s_mov_b32 m0, s18
	s_nop 0
	global_load_lds_dwordx4 v[216:217], off
	s_waitcnt vmcnt(8)
	s_waitcnt lgkmcnt(0)
	s_barrier
; #define PG8_STAGE(bufoff, gbase, voff) do { _Pragma("unroll") for (int _i = 0; _i < 2; ++_i) \
;         __builtin_amdgcn_global_load_lds((const unsigned*)((const char*)(gbase) + (voff)[_i]), (LAS unsigned*)(lds + (bufoff) + ldsw + _i * 8192), 16, 0, 0); } while (0)
; #define PG8_LDA(dst, b, h) do { _Pragma("unroll") for (int m = 0; m < 4; ++m) _Pragma("unroll") for (int k = 0; k < 2; ++k) dst[m][k] = *(const LAS bf16x8*)(lds + PG8_SA(b, h) + aoff + m * 2048 + k * 1024); } while (0)
; #define PG8_LDB(dst, b, h) do { _Pragma("unroll") for (int n = 0; n < 2; ++n) _Pragma("unroll") for (int k = 0; k < 2; ++k) dst[n][k] = *(const LAS bf16x8*)(lds + PG8_SB(b, h) + boff + n * 2048 + k * 1024); } while (0)
; #define PG8_MMA(ai, bj, At, Bt) do { __builtin_amdgcn_s_setprio(1); _Pragma("unroll") for (int m = 0; m < 4; ++m) _Pragma("unroll") for (int n = 0; n < 2; ++n) _Pragma("unroll") for (int k = 0; k < 2; ++k) \
;         acc[ai][bj][m][n] = __builtin_amdgcn_mfma_f32_16x16x32_bf16(Bt[n][k], At[m][k], acc[ai][bj][m][n], 0, 0, 0); __builtin_amdgcn_s_setprio(0); } while (0)
; #define PG8_WAIT_V(n) asm volatile("s_waitcnt vmcnt(" #n ")" ::: "memory")
; #define PG8_WAIT_L(n) asm volatile("s_waitcnt lgkmcnt(" #n ")" ::: "memory")
; #define PG8_BAR __builtin_amdgcn_s_barrier()
; #define PG8_SCHED __builtin_amdgcn_sched_barrier(0)
; template <class Epi, class Sched>
; __device__ __forceinline__ void gemm_phase(LAS unsigned char* lds, const Gemm g, Sched S, const Epi& E) {
;     ...
;             PG8_LDB(B0, 0, 0); PG8_LDB(B1, 0, 1); PG8_SCHED; PG8_LDA(At, 0, 0); PG8_STAGE(PG8_SA(1, 1), a1 + hstepA, voffA);
;             PG8_WAIT_V(8); PG8_WAIT_L(0); PG8_BAR; PG8_MMA(0, 0, At, B0); PG8_MMA(0, 1, At, B1); PG8_BAR; PG8_SCHED;
;             PG8_LDA(At, 0, 1); PG8_STAGE(PG8_SB(0, 0), b2, voffB); PG8_STAGE(PG8_SB(0, 1), b2 + hstepB, voffB); PG8_STAGE(PG8_SA(0, 0), a2, voffA);
;             PG8_WAIT_V(8); PG8_WAIT_L(0); PG8_BAR; PG8_MMA(1, 0, At, B0); PG8_MMA(1, 1, At, B1); PG8_BAR; PG8_SCHED;
	s_setprio 1
	s_waitcnt lgkmcnt(0)
	v_mfma_f32_16x16x32_bf16 v[66:69], v[106:109], v[176:179], v[66:69]
	v_mfma_f32_16x16x32_bf16 v[70:73], v[114:117], v[176:179], v[70:73]
	v_mfma_f32_16x16x32_bf16 v[74:77], v[106:109], v[192:195], v[74:77]
	v_mfma_f32_16x16x32_bf16 v[78:81], v[114:117], v[192:195], v[78:81]
	v_mfma_f32_16x16x32_bf16 v[82:85], v[106:109], v[200:203], v[82:85]
	v_mfma_f32_16x16x32_bf16 v[86:89], v[114:117], v[200:203], v[86:89]
	v_mfma_f32_16x16x32_bf16 v[90:93], v[106:109], v[208:211], v[90:93]
	v_mfma_f32_16x16x32_bf16 v[66:69], v[110:113], v[180:183], v[66:69]
	v_mfma_f32_16x16x32_bf16 v[70:73], v[118:121], v[180:183], v[70:73]
	v_mfma_f32_16x16x32_bf16 v[74:77], v[110:113], v[196:199], v[74:77]
	v_mfma_f32_16x16x32_bf16 v[78:81], v[118:121], v[196:199], v[78:81]
	v_mfma_f32_16x16x32_bf16 v[82:85], v[110:113], v[204:207], v[82:85]
	v_mfma_f32_16x16x32_bf16 v[86:89], v[118:121], v[204:207], v[86:89]
	v_mfma_f32_16x16x32_bf16 v[90:93], v[110:113], v[212:215], v[90:93]
	v_mfma_f32_16x16x32_bf16 v[94:97], v[114:117], v[208:211], v[94:97]
	v_mfma_f32_16x16x32_bf16 v[216:219], v[118:121], v[212:215], v[94:97]
	s_setprio 0
	s_setprio 1
	v_mfma_f32_16x16x32_bf16 v[94:97], v[122:125], v[176:179], v[98:101]
	v_mfma_f32_16x16x32_bf16 v[34:37], v[168:171], v[176:179], v[34:37]
	v_mfma_f32_16x16x32_bf16 v[38:41], v[122:125], v[192:195], v[38:41]
	v_mfma_f32_16x16x32_bf16 v[42:45], v[168:171], v[192:195], v[42:45]
	v_mfma_f32_16x16x32_bf16 v[46:49], v[122:125], v[200:203], v[46:49]
	v_mfma_f32_16x16x32_bf16 v[50:53], v[168:171], v[200:203], v[50:53]
	v_mfma_f32_16x16x32_bf16 v[54:57], v[122:125], v[208:211], v[54:57]
	v_mfma_f32_16x16x32_bf16 v[58:61], v[168:171], v[208:211], v[58:61]
	v_mfma_f32_16x16x32_bf16 v[98:101], v[126:129], v[180:183], v[94:97]
	v_mfma_f32_16x16x32_bf16 v[34:37], v[172:175], v[180:183], v[34:37]
	v_mfma_f32_16x16x32_bf16 v[38:41], v[126:129], v[196:199], v[38:41]
	v_mfma_f32_16x16x32_bf16 v[42:45], v[172:175], v[196:199], v[42:45]
	s_setprio 2
	s_barrier
	v_mfma_f32_16x16x32_bf16 v[46:49], v[126:129], v[204:207], v[46:49]
	v_mfma_f32_16x16x32_bf16 v[50:53], v[172:175], v[204:207], v[50:53]
	v_mfma_f32_16x16x32_bf16 v[54:57], v[126:129], v[212:215], v[54:57]
	v_mfma_f32_16x16x32_bf16 v[58:61], v[172:175], v[212:215], v[58:61]
	s_setprio 0
	s_mov_b32 m0, s40
	v_lshl_add_u64 v[248:249], s[52:53], 0, v[0:1]
	s_add_u32 s2, s52, 0x40000
	ds_read_b128 v[94:97], v153 offset:16384
	ds_read_b128 v[176:179], v153 offset:17408
	ds_read_b128 v[180:183], v153 offset:18432
	ds_read_b128 v[192:195], v153 offset:19456
	ds_read_b128 v[196:199], v153 offset:20480
	ds_read_b128 v[200:203], v153 offset:21504
	ds_read_b128 v[204:207], v153 offset:22528
	ds_read_b128 v[208:211], v153 offset:23552
	global_load_lds_dwordx4 v[248:249], off
	v_lshl_add_u64 v[250:251], s[52:53], 0, v[130:131]
	s_mov_b32 m0, s19
	s_addc_u32 s3, s53, 0
	global_load_lds_dwordx4 v[250:251], off
	v_lshl_add_u64 v[212:213], s[2:3], 0, v[0:1]
	s_mov_b32 m0, s31
	v_lshl_add_u64 v[252:253], s[66:67], 0, v[134:135]
	global_load_lds_dwordx4 v[212:213], off
	v_lshl_add_u64 v[212:213], s[2:3], 0, v[130:131]
	s_mov_b32 m0, s35
	v_lshl_add_u64 v[190:191], s[66:67], 0, v[132:133]
	global_load_lds_dwordx4 v[212:213], off
	s_mov_b32 m0, s43
	s_nop 0
	global_load_lds_dwordx4 v[252:253], off
	s_mov_b32 m0, s45
	s_nop 0
	global_load_lds_dwordx4 v[190:191], off
	s_waitcnt vmcnt(8)
	s_waitcnt lgkmcnt(0)
	s_barrier
	s_setprio 1
	s_waitcnt lgkmcnt(0)
	v_mfma_f32_16x16x32_bf16 v[2:5], v[106:109], v[204:207], v[2:5]
	v_mfma_f32_16x16x32_bf16 v[6:9], v[114:117], v[204:207], v[6:9]
	v_mfma_f32_16x16x32_bf16 v[136:139], v[106:109], v[94:97], v[136:139]
	v_mfma_f32_16x16x32_bf16 v[140:143], v[114:117], v[94:97], v[140:143]
	v_mfma_f32_16x16x32_bf16 v[144:147], v[106:109], v[180:183], v[144:147]
	v_mfma_f32_16x16x32_bf16 v[154:157], v[114:117], v[180:183], v[154:157]
	v_mfma_f32_16x16x32_bf16 v[158:161], v[106:109], v[196:199], v[158:161]
	v_mfma_f32_16x16x32_bf16 v[164:167], v[114:117], v[196:199], v[164:167]
	v_mfma_f32_16x16x32_bf16 v[2:5], v[110:113], v[208:211], v[2:5]
	v_mfma_f32_16x16x32_bf16 v[6:9], v[118:121], v[208:211], v[6:9]
	v_mfma_f32_16x16x32_bf16 v[136:139], v[110:113], v[176:179], v[136:139]
	v_mfma_f32_16x16x32_bf16 v[140:143], v[118:121], v[176:179], v[140:143]
	v_mfma_f32_16x16x32_bf16 v[144:147], v[110:113], v[192:195], v[144:147]
	v_mfma_f32_16x16x32_bf16 v[154:157], v[118:121], v[192:195], v[154:157]
	v_mfma_f32_16x16x32_bf16 v[158:161], v[110:113], v[200:203], v[158:161]
	v_mfma_f32_16x16x32_bf16 v[164:167], v[118:121], v[200:203], v[164:167]
	s_setprio 0
	s_setprio 1
	v_mfma_f32_16x16x32_bf16 v[10:13], v[122:125], v[94:97], v[10:13]
	v_mfma_f32_16x16x32_bf16 v[14:17], v[168:171], v[94:97], v[14:17]
	v_mfma_f32_16x16x32_bf16 v[10:13], v[126:129], v[176:179], v[10:13]
	v_mfma_f32_16x16x32_bf16 v[176:179], v[172:175], v[176:179], v[14:17]
	v_mfma_f32_16x16x32_bf16 v[14:17], v[122:125], v[180:183], v[26:29]
	v_mfma_f32_16x16x32_bf16 v[26:29], v[126:129], v[192:195], v[14:17]
	v_mfma_f32_16x16x32_bf16 v[14:17], v[168:171], v[180:183], v[30:33]
	v_mfma_f32_16x16x32_bf16 v[180:183], v[172:175], v[192:195], v[14:17]
	v_mfma_f32_16x16x32_bf16 v[14:17], v[122:125], v[196:199], v[62:65]
	v_mfma_f32_16x16x32_bf16 v[192:195], v[126:129], v[200:203], v[14:17]
	v_mfma_f32_16x16x32_bf16 v[14:17], v[168:171], v[196:199], v[102:105]
	v_mfma_f32_16x16x32_bf16 v[196:199], v[172:175], v[200:203], v[14:17]
	s_setprio 2
	s_barrier
; #define PG8_STAGE(bufoff, gbase, voff) do { _Pragma("unroll") for (int _i = 0; _i < 2; ++_i) \
;         __builtin_amdgcn_global_load_lds((const unsigned*)((const char*)(gbase) + (voff)[_i]), (LAS unsigned*)(lds + (bufoff) + ldsw + _i * 8192), 16, 0, 0); } while (0)
; #define PG8_LDA(dst, b, h) do { _Pragma("unroll") for (int m = 0; m < 4; ++m) _Pragma("unroll") for (int k = 0; k < 2; ++k) dst[m][k] = *(const LAS bf16x8*)(lds + PG8_SA(b, h) + aoff + m * 2048 + k * 1024); } while (0)
; #define PG8_LDB(dst, b, h) do { _Pragma("unroll") for (int n = 0; n < 2; ++n) _Pragma("unroll") for (int k = 0; k < 2; ++k) dst[n][k] = *(const LAS bf16x8*)(lds + PG8_SB(b, h) + boff + n * 2048 + k * 1024); } while (0)
; #define PG8_MMA(ai, bj, At, Bt) do { __builtin_amdgcn_s_setprio(1); _Pragma("unroll") for (int m = 0; m < 4; ++m) _Pragma("unroll") for (int n = 0; n < 2; ++n) _Pragma("unroll") for (int k = 0; k < 2; ++k) \
;         acc[ai][bj][m][n] = __builtin_amdgcn_mfma_f32_16x16x32_bf16(Bt[n][k], At[m][k], acc[ai][bj][m][n], 0, 0, 0); __builtin_amdgcn_s_setprio(0); } while (0)
; #define PG8_WAIT_V(n) asm volatile("s_waitcnt vmcnt(" #n ")" ::: "memory")
; #define PG8_WAIT_L(n) asm volatile("s_waitcnt lgkmcnt(" #n ")" ::: "memory")
; #define PG8_BAR __builtin_amdgcn_s_barrier()
; #define PG8_SCHED __builtin_amdgcn_sched_barrier(0)
; template <class Epi, class Sched>
; __device__ __forceinline__ void gemm_phase(LAS unsigned char* lds, const Gemm g, Sched S, const Epi& E) {
;     ...
;             PG8_LDB(B0, 1, 0); PG8_LDB(B1, 1, 1); PG8_SCHED; PG8_LDA(At, 1, 0); PG8_STAGE(PG8_SA(0, 1), a2 + hstepA, voffA);
;             PG8_WAIT_V(8); PG8_WAIT_L(0); PG8_BAR; PG8_MMA(0, 0, At, B0); PG8_MMA(0, 1, At, B1); PG8_BAR; PG8_SCHED;
;             PG8_LDA(At, 1, 1); PG8_STAGE(PG8_SB(1, 0), b3, voffB); PG8_STAGE(PG8_SB(1, 1), b3 + hstepB, voffB); PG8_STAGE(PG8_SA(1, 0), a3, voffA);
;             PG8_WAIT_V(8); PG8_WAIT_L(0); PG8_BAR; PG8_MMA(1, 0, At, B0); PG8_MMA(1, 1, At, B1); PG8_BAR; PG8_SCHED;
;     ...
;         if (wr == 0) PG8_BAR;
	v_mfma_f32_16x16x32_bf16 v[14:17], v[122:125], v[204:207], v[18:21]
	v_mfma_f32_16x16x32_bf16 v[200:203], v[126:129], v[208:211], v[14:17]
	v_mfma_f32_16x16x32_bf16 v[14:17], v[168:171], v[204:207], v[22:25]
	v_mfma_f32_16x16x32_bf16 v[168:171], v[172:175], v[208:211], v[14:17]
	s_setprio 0
	s_nop 4
	ds_read_b128 v[14:17], v226
	ds_read_b128 v[18:21], v226 offset:1024
	ds_read_b128 v[172:175], v226 offset:2048
	ds_read_b128 v[204:207], v226 offset:3072
	ds_read_b128 v[208:211], v227
	ds_read_b128 v[212:215], v227 offset:1024
	ds_read_b128 v[220:223], v227 offset:2048
	ds_read_b128 v[224:227], v227 offset:3072
	s_add_u32 s2, s66, 0x40000
	s_addc_u32 s3, s67, 0
	s_mov_b32 m0, s84
	v_lshl_add_u64 v[94:95], s[2:3], 0, v[134:135]
	ds_read_b128 v[22:25], v153 offset:32768
	ds_read_b128 v[30:33], v153 offset:33792
	ds_read_b128 v[62:65], v153 offset:34816
	ds_read_b128 v[228:231], v153 offset:35840
	ds_read_b128 v[232:235], v153 offset:36864
	ds_read_b128 v[236:239], v153 offset:37888
	ds_read_b128 v[240:243], v153 offset:38912
	ds_read_b128 v[244:247], v153 offset:39936
	global_load_lds_dwordx4 v[94:95], off
	v_lshl_add_u64 v[94:95], s[2:3], 0, v[132:133]
	s_mov_b32 m0, s94
	s_nop 0
	global_load_lds_dwordx4 v[94:95], off
	s_waitcnt vmcnt(8)
	s_waitcnt lgkmcnt(0)
	s_barrier
	s_setprio 1
	s_waitcnt lgkmcnt(0)
	v_mfma_f32_16x16x32_bf16 v[66:69], v[14:17], v[22:25], v[66:69]
	v_mfma_f32_16x16x32_bf16 v[126:129], v[18:21], v[30:33], v[66:69]
	v_mfma_f32_16x16x32_bf16 v[66:69], v[172:175], v[22:25], v[70:73]
	v_mfma_f32_16x16x32_bf16 v[118:121], v[204:207], v[30:33], v[66:69]
	v_mfma_f32_16x16x32_bf16 v[66:69], v[14:17], v[62:65], v[74:77]
	v_mfma_f32_16x16x32_bf16 v[110:113], v[18:21], v[228:231], v[66:69]
	v_mfma_f32_16x16x32_bf16 v[66:69], v[172:175], v[62:65], v[78:81]
	v_mfma_f32_16x16x32_bf16 v[102:105], v[204:207], v[228:231], v[66:69]
	v_mfma_f32_16x16x32_bf16 v[66:69], v[14:17], v[232:235], v[82:85]
	v_mfma_f32_16x16x32_bf16 v[94:97], v[18:21], v[236:239], v[66:69]
	v_mfma_f32_16x16x32_bf16 v[66:69], v[172:175], v[232:235], v[86:89]
	v_mfma_f32_16x16x32_bf16 v[86:89], v[204:207], v[236:239], v[66:69]
	v_mfma_f32_16x16x32_bf16 v[66:69], v[14:17], v[240:243], v[90:93]
	v_mfma_f32_16x16x32_bf16 v[78:81], v[18:21], v[244:247], v[66:69]
	v_mfma_f32_16x16x32_bf16 v[66:69], v[172:175], v[240:243], v[216:219]
	v_mfma_f32_16x16x32_bf16 v[70:73], v[204:207], v[244:247], v[66:69]
	s_setprio 0
	s_setprio 1
	v_mfma_f32_16x16x32_bf16 v[66:69], v[208:211], v[22:25], v[98:101]
	v_mfma_f32_16x16x32_bf16 v[22:25], v[220:223], v[22:25], v[34:37]
	v_mfma_f32_16x16x32_bf16 v[114:117], v[224:227], v[30:33], v[22:25]
	v_mfma_f32_16x16x32_bf16 v[22:25], v[208:211], v[62:65], v[38:41]
	v_mfma_f32_16x16x32_bf16 v[106:109], v[212:215], v[228:231], v[22:25]
	v_mfma_f32_16x16x32_bf16 v[22:25], v[220:223], v[62:65], v[42:45]
	v_mfma_f32_16x16x32_bf16 v[98:101], v[224:227], v[228:231], v[22:25]
	v_mfma_f32_16x16x32_bf16 v[22:25], v[208:211], v[232:235], v[46:49]
	v_mfma_f32_16x16x32_bf16 v[90:93], v[212:215], v[236:239], v[22:25]
	v_mfma_f32_16x16x32_bf16 v[22:25], v[220:223], v[232:235], v[50:53]
	v_mfma_f32_16x16x32_bf16 v[82:85], v[224:227], v[236:239], v[22:25]
	v_mfma_f32_16x16x32_bf16 v[22:25], v[208:211], v[240:243], v[54:57]
	s_setprio 2
	s_barrier
	v_mfma_f32_16x16x32_bf16 v[74:77], v[212:215], v[244:247], v[22:25]
	v_mfma_f32_16x16x32_bf16 v[22:25], v[220:223], v[240:243], v[58:61]
	v_mfma_f32_16x16x32_bf16 v[122:125], v[212:215], v[30:33], v[66:69]
	v_mfma_f32_16x16x32_bf16 v[66:69], v[224:227], v[244:247], v[22:25]
	s_setprio 0
	s_mov_b32 m0, s60
	s_nop 2
	v_lshl_add_u64 v[22:23], v[248:249], 0, s[74:75]
	s_add_u32 s2, s52, 0x40080
	ds_read_b128 v[34:37], v153 offset:49152
	ds_read_b128 v[42:45], v153 offset:50176
	ds_read_b128 v[216:219], v153 offset:51200
	ds_read_b128 v[228:231], v153 offset:52224
	ds_read_b128 v[232:235], v153 offset:53248
	ds_read_b128 v[236:239], v153 offset:54272
	ds_read_b128 v[240:243], v153 offset:55296
	ds_read_b128 v[244:247], v153 offset:56320
	global_load_lds_dwordx4 v[22:23], off
	v_lshl_add_u64 v[22:23], v[250:251], 0, s[74:75]
	s_mov_b32 m0, s58
	s_addc_u32 s3, s53, 0
	global_load_lds_dwordx4 v[22:23], off
	v_lshl_add_u64 v[22:23], s[2:3], 0, v[0:1]
	s_mov_b32 m0, s54
	s_nop 0
	global_load_lds_dwordx4 v[22:23], off
	v_lshl_add_u64 v[22:23], s[2:3], 0, v[130:131]
	s_mov_b32 m0, s55
	s_nop 0
	global_load_lds_dwordx4 v[22:23], off
	v_lshl_add_u64 v[22:23], v[252:253], 0, s[74:75]
	s_mov_b32 m0, s96
	s_nop 0
	global_load_lds_dwordx4 v[22:23], off
	v_lshl_add_u64 v[22:23], v[190:191], 0, s[74:75]
	s_mov_b32 m0, s97
	s_nop 0
	global_load_lds_dwordx4 v[22:23], off
	s_waitcnt vmcnt(8)
	s_waitcnt lgkmcnt(0)
	s_barrier
	s_setprio 1
	s_waitcnt lgkmcnt(0)
	v_mfma_f32_16x16x32_bf16 v[22:25], v[14:17], v[34:37], v[136:139]
	v_mfma_f32_16x16x32_bf16 v[62:65], v[18:21], v[42:45], v[22:25]
	v_mfma_f32_16x16x32_bf16 v[22:25], v[172:175], v[34:37], v[140:143]
	v_mfma_f32_16x16x32_bf16 v[54:57], v[204:207], v[42:45], v[22:25]
	v_mfma_f32_16x16x32_bf16 v[22:25], v[14:17], v[216:219], v[144:147]
	v_mfma_f32_16x16x32_bf16 v[46:49], v[18:21], v[228:231], v[22:25]
	v_mfma_f32_16x16x32_bf16 v[22:25], v[172:175], v[216:219], v[154:157]
	v_mfma_f32_16x16x32_bf16 v[38:41], v[204:207], v[228:231], v[22:25]
	v_mfma_f32_16x16x32_bf16 v[22:25], v[14:17], v[232:235], v[158:161]
	v_mfma_f32_16x16x32_bf16 v[2:5], v[14:17], v[240:243], v[2:5]
	v_mfma_f32_16x16x32_bf16 v[30:33], v[18:21], v[236:239], v[22:25]
	v_mfma_f32_16x16x32_bf16 v[22:25], v[172:175], v[232:235], v[164:167]
	v_mfma_f32_16x16x32_bf16 v[14:17], v[18:21], v[244:247], v[2:5]
	v_mfma_f32_16x16x32_bf16 v[2:5], v[172:175], v[240:243], v[6:9]
	v_mfma_f32_16x16x32_bf16 v[22:25], v[204:207], v[236:239], v[22:25]
	v_mfma_f32_16x16x32_bf16 v[6:9], v[204:207], v[244:247], v[2:5]
	s_setprio 0
	s_setprio 1
	v_mfma_f32_16x16x32_bf16 v[2:5], v[208:211], v[34:37], v[10:13]
	v_mfma_f32_16x16x32_bf16 v[58:61], v[212:215], v[42:45], v[2:5]
	v_mfma_f32_16x16x32_bf16 v[2:5], v[220:223], v[34:37], v[176:179]
	v_mfma_f32_16x16x32_bf16 v[50:53], v[224:227], v[42:45], v[2:5]
	v_mfma_f32_16x16x32_bf16 v[2:5], v[208:211], v[216:219], v[26:29]
	v_mfma_f32_16x16x32_bf16 v[42:45], v[212:215], v[228:231], v[2:5]
	v_mfma_f32_16x16x32_bf16 v[2:5], v[220:223], v[216:219], v[180:183]
	v_mfma_f32_16x16x32_bf16 v[34:37], v[224:227], v[228:231], v[2:5]
	v_mfma_f32_16x16x32_bf16 v[2:5], v[208:211], v[232:235], v[192:195]
	v_mfma_f32_16x16x32_bf16 v[26:29], v[212:215], v[236:239], v[2:5]
	v_mfma_f32_16x16x32_bf16 v[2:5], v[220:223], v[232:235], v[196:199]
	v_mfma_f32_16x16x32_bf16 v[18:21], v[224:227], v[236:239], v[2:5]
	s_setprio 2
	s_barrier
	v_mfma_f32_16x16x32_bf16 v[2:5], v[208:211], v[240:243], v[200:203]
	v_mfma_f32_16x16x32_bf16 v[10:13], v[212:215], v[244:247], v[2:5]
	v_mfma_f32_16x16x32_bf16 v[2:5], v[220:223], v[240:243], v[168:171]
	v_mfma_f32_16x16x32_bf16 v[2:5], v[224:227], v[244:247], v[2:5]
	s_setprio 0
	s_andn2_b64 vcc, exec, s[8:9]
	s_cbranch_vccnz .LBB0_516
	s_barrier
